# polling cadence: s_sleep 0 instead of s_sleep 1 in the grid-barrier and partner hand-off spin loops
# speedup vs baseline: 1.0036x; 1.0036x over previous
; __device__ __forceinline__ bool xb_leader(int wave) { int l_ = (int)__builtin_amdgcn_mbcnt_hi(~0u, __builtin_amdgcn_mbcnt_lo(~0u, 0u)); asm volatile("" : "+v"(l_)); return wave == 0 && l_ == 0; }
; __global__ void __launch_bounds__(NTHREADS, 2) mega_fwd(Args args) {
;     ...
;         const bool ldr = xb_leader(wave);
;         if (ldr) { __builtin_amdgcn_fence(__ATOMIC_RELEASE, "agent"); asm volatile("s_waitcnt vmcnt(0)" ::: "memory"); }
;         grid.sync();
;         if (ldr) { __builtin_amdgcn_fence(__ATOMIC_ACQUIRE, "agent"); asm volatile("s_waitcnt vmcnt(0)" ::: "memory"); }
.LBB0_194:
	s_sleep 0
	global_load_dword v2, v0, s[2:3] offset:32 sc1
	s_waitcnt vmcnt(0)
	v_and_b32_e32 v2, 0xffff0000, v2
	v_cmp_ne_u32_e32 vcc, v2, v1
	s_or_b64 s[8:9], vcc, s[8:9]
	s_andn2_b64 exec, exec, s[8:9]
	s_cbranch_execnz .LBB0_194

; __device__ __forceinline__ unsigned xb_ld(unsigned* p)              { return __hip_atomic_load(p, __ATOMIC_RELAXED, __HIP_MEMORY_SCOPE_AGENT); }
; __device__ __forceinline__ void xcd_barrier_complete(unsigned* bar, unsigned x, unsigned& nloc, unsigned& nx) {
;     ...
;     for (;;) {
;         sum = 0u; cnt = 0u; mine = 0u;
; #pragma unroll
;         for (unsigned j = 0; j < 16; ++j) { const unsigned c = xb_ld(&bar[XB_XCNT(j)]); sum += c; cnt += (c > 0u) ? 1u : 0u; mine = (j == x) ? c : mine; }
;         if (sum == G) break;
;         __builtin_amdgcn_s_sleep(1);
;         if ((++sp & 255u) == 0u) { if (xb_ld(&bar[XB_TMO])) break; if (sp > XB_SPIN_CAP) { atomicAdd(&bar[XB_TMO], 1u); break; } }
;     }
.LBB0_239:
	v_readlane_b32 s2, v254, 6
	v_readlane_b32 s3, v254, 7
	s_waitcnt lgkmcnt(0)
	global_load_dword v0, v97, s[58:59] sc1
	s_mov_b64 s[14:15], -1
	s_nop 1
	global_load_dword v1, v97, s[2:3] sc1
	v_readlane_b32 s2, v254, 8
	v_readlane_b32 s3, v254, 9
	s_waitcnt vmcnt(0)
	v_add_u32_e32 v16, v1, v0
	s_nop 2
	global_load_dword v2, v97, s[2:3] sc1
	v_readlane_b32 s2, v254, 10
	v_readlane_b32 s3, v254, 11
	s_waitcnt vmcnt(0)
	v_add_u32_e32 v16, v16, v2
	s_nop 2
	global_load_dword v3, v97, s[2:3] sc1
	v_readlane_b32 s2, v254, 12
	v_readlane_b32 s3, v254, 13
	s_waitcnt vmcnt(0)
	v_add_u32_e32 v16, v16, v3
	s_nop 2
	global_load_dword v4, v97, s[2:3] sc1
	v_readlane_b32 s2, v254, 14
	v_readlane_b32 s3, v254, 15
	s_waitcnt vmcnt(0)
	v_add_u32_e32 v16, v16, v4
	s_nop 2
	global_load_dword v5, v97, s[2:3] sc1
	v_readlane_b32 s2, v254, 16
	v_readlane_b32 s3, v254, 17
	s_waitcnt vmcnt(0)
	v_add_u32_e32 v16, v16, v5
	s_nop 2
	global_load_dword v6, v97, s[2:3] sc1
	v_readlane_b32 s2, v254, 18
	v_readlane_b32 s3, v254, 19
	s_waitcnt vmcnt(0)
	v_add_u32_e32 v16, v16, v6
	s_nop 2
	global_load_dword v7, v97, s[2:3] sc1
	v_readlane_b32 s2, v254, 20
	v_readlane_b32 s3, v254, 21
	s_waitcnt vmcnt(0)
	v_add_u32_e32 v16, v16, v7
	s_nop 2
	global_load_dword v8, v97, s[2:3] sc1
	v_readlane_b32 s2, v254, 22
	v_readlane_b32 s3, v254, 23
	s_waitcnt vmcnt(0)
	v_add_u32_e32 v16, v16, v8
	s_nop 2
	global_load_dword v9, v97, s[2:3] sc1
	v_readlane_b32 s2, v254, 24
	v_readlane_b32 s3, v254, 25
	s_waitcnt vmcnt(0)
	v_add_u32_e32 v16, v16, v9
	s_nop 2
	global_load_dword v10, v97, s[2:3] sc1
	v_readlane_b32 s2, v254, 26
	v_readlane_b32 s3, v254, 27
	s_waitcnt vmcnt(0)
	v_add_u32_e32 v16, v16, v10
	s_nop 2
	global_load_dword v11, v97, s[2:3] sc1
	v_readlane_b32 s2, v254, 28
	v_readlane_b32 s3, v254, 29
	s_waitcnt vmcnt(0)
	v_add_u32_e32 v16, v16, v11
	s_nop 2
	global_load_dword v12, v97, s[2:3] sc1
	v_readlane_b32 s2, v254, 30
	v_readlane_b32 s3, v254, 31
	s_waitcnt vmcnt(0)
	v_add_u32_e32 v16, v16, v12
	s_nop 2
	global_load_dword v13, v97, s[2:3] sc1
	v_readlane_b32 s2, v254, 32
	v_readlane_b32 s3, v254, 33
	s_waitcnt vmcnt(0)
	v_add_u32_e32 v16, v16, v13
	s_nop 2
	global_load_dword v14, v97, s[2:3] sc1
	v_readlane_b32 s2, v254, 34
	v_readlane_b32 s3, v254, 35
	s_waitcnt vmcnt(0)
	v_add_u32_e32 v16, v16, v14
	s_nop 2
	global_load_dword v15, v97, s[2:3] sc1
	s_mov_b64 s[2:3], -1
	s_waitcnt vmcnt(0)
	v_add_u32_e32 v16, v16, v15
	v_cmp_eq_u32_e32 vcc, s36, v16
	s_cbranch_vccnz .LBB0_238
	s_and_b32 s2, s6, 0xff
	s_cmp_eq_u32 s2, 0
	s_mov_b64 s[2:3], -1
	s_mov_b64 s[16:17], -1
	s_sleep 0
	s_cbranch_scc1 .LBB0_243
	s_and_b64 vcc, exec, s[16:17]
	s_cbranch_vccz .LBB0_238

; __device__ __forceinline__ unsigned xb_ld(unsigned* p)              { return __hip_atomic_load(p, __ATOMIC_RELAXED, __HIP_MEMORY_SCOPE_AGENT); }
; __device__ __forceinline__ unsigned xb_add(unsigned* p, unsigned v) { return __hip_atomic_fetch_add(p, v, __ATOMIC_RELAXED, __HIP_MEMORY_SCOPE_AGENT); }
; #define XB_SPIN(cond, bar) do { unsigned _sp = 0; while (cond) { __builtin_amdgcn_s_sleep(1); \
;     if ((++_sp & 255u) == 0u) { if (xb_ld(&(bar)[XB_TMO])) break; if (_sp > XB_SPIN_CAP) { atomicAdd(&(bar)[XB_TMO], 1u); break; } } } } while (0)
; __device__ __forceinline__ void xcd_barrier(const XcdBarrier& b, int wave) {
;     ...
;             else XB_SPIN(xb_ld(&bar[XB_TOPGEN]) == tg, bar);
;             __builtin_amdgcn_fence(__ATOMIC_ACQUIRE, "agent");
;             xb_add(&bar[XB_XGEN(b.x)], 1u);
;             asm volatile("s_waitcnt vmcnt(0)" ::: "memory");
;         } else {
;             XB_SPIN(xb_ld(&bar[XB_XGEN(b.x)]) == gen, bar);
.LBB0_257:
	s_and_b32 s7, s6, 0xff
	s_mov_b64 s[26:27], -1
	s_cmp_lg_u32 s7, 0
	s_mov_b64 s[30:31], -1
	s_sleep 0
	s_cbranch_scc0 .LBB0_260
	s_and_b64 vcc, exec, s[30:31]
	s_cbranch_vccz .LBB0_256

; __global__ void __launch_bounds__(NTHREADS, 2) mega_fwd(Args args) {
;     ...
;                     if (wavep == 0 && lane == 0) {
;                         unsigned* flg = (unsigned*)(ws + WS_BAR) + 4096 + l * 256;
;                         __hip_atomic_store(flg + unit, 1u, __ATOMIC_RELAXED, __HIP_MEMORY_SCOPE_AGENT);
;                         unsigned spins = 0;
;                         while (__hip_atomic_load(flg + (unit ^ 8), __ATOMIC_RELAXED, __HIP_MEMORY_SCOPE_AGENT) == 0u) { __builtin_amdgcn_s_sleep(1); if (++spins > (1u << 20)) break; }
;                         __builtin_amdgcn_fence(__ATOMIC_ACQUIRE, "agent");
;                         asm volatile("s_waitcnt vmcnt(0)" ::: "memory");
;                     }
.LBB0_582:
	v_mov_b64_e32 v[0:1], s[30:31]
	flat_load_dword v0, v[0:1] sc1
	s_or_b64 s[80:81], s[80:81], exec
	s_waitcnt vmcnt(0) lgkmcnt(0)
	v_cmp_eq_u32_e32 vcc, 0, v0
	s_and_saveexec_b64 s[82:83], vcc
	s_cbranch_execz .LBB0_581
	s_cmp_lg_u32 s27, 0
	s_sleep 0
	s_cbranch_scc0 .LBB0_592
	v_mov_b64_e32 v[0:1], s[30:31]
	flat_load_dword v0, v[0:1] sc1
	s_mov_b64 s[86:87], -1
	s_waitcnt vmcnt(0) lgkmcnt(0)
	v_cmp_eq_u32_e32 vcc, 0, v0
	s_and_saveexec_b64 s[84:85], vcc
	s_cbranch_execz .LBB0_579
	v_mov_b64_e32 v[0:1], s[30:31]
	s_sleep 0
	flat_load_dword v0, v[0:1] sc1
	s_mov_b64 s[88:89], -1
	s_waitcnt vmcnt(0) lgkmcnt(0)
	v_cmp_eq_u32_e32 vcc, 0, v0
	s_and_saveexec_b64 s[86:87], vcc
	s_cbranch_execz .LBB0_578
	v_mov_b64_e32 v[0:1], s[30:31]
	s_sleep 0
	flat_load_dword v0, v[0:1] sc1
	s_mov_b64 s[90:91], -1
	s_waitcnt vmcnt(0) lgkmcnt(0)
	v_cmp_eq_u32_e32 vcc, 0, v0
	s_and_saveexec_b64 s[88:89], vcc
	s_cbranch_execz .LBB0_577
	v_mov_b64_e32 v[0:1], s[30:31]
	s_sleep 0
	flat_load_dword v0, v[0:1] sc1
	s_mov_b64 s[92:93], -1
	s_waitcnt vmcnt(0) lgkmcnt(0)
	v_cmp_eq_u32_e32 vcc, 0, v0
	s_and_saveexec_b64 s[90:91], vcc
	s_cbranch_execz .LBB0_576
	v_mov_b64_e32 v[0:1], s[30:31]
	s_sleep 0
	flat_load_dword v0, v[0:1] sc1
	s_mov_b64 s[94:95], -1
	s_waitcnt vmcnt(0) lgkmcnt(0)
	v_cmp_eq_u32_e32 vcc, 0, v0
	s_and_saveexec_b64 s[92:93], vcc
	s_cbranch_execz .LBB0_575
	v_mov_b64_e32 v[0:1], s[30:31]
	s_sleep 0
	flat_load_dword v0, v[0:1] sc1
	s_mov_b64 s[96:97], -1
	s_waitcnt vmcnt(0) lgkmcnt(0)
	v_cmp_eq_u32_e32 vcc, 0, v0
	s_and_saveexec_b64 s[94:95], vcc
	s_cbranch_execz .LBB0_574
	v_mov_b64_e32 v[0:1], s[30:31]
	s_sleep 0
	flat_load_dword v0, v[0:1] sc1
	s_waitcnt vmcnt(0) lgkmcnt(0)
	v_cmp_eq_u32_e32 vcc, 0, v0
	s_and_saveexec_b64 s[40:41], vcc
	s_cbranch_execz .LBB0_573
	s_add_i32 s27, s27, -8
	s_xor_b64 s[96:97], exec, -1
	s_sleep 0
	s_branch .LBB0_573
